# NA: K/V fragment loads of edge query groups (j=0,3) run with the always-masked key group's lanes disabled (V dead lanes zeroed)
# speedup vs baseline: 1.0103x; 1.0103x over previous
; #define LAS __attribute__((address_space(3)))
; __device__ __forceinline__ void na_phase(const Frame& F, const bf16* QH, const bf16* VB, const float* rpb, bf16* U) {
;     ...
;     LAS float* RP = (LAS float*)F.lds;
;     for (int i = F.tid; i < 16 * 465; i += 512) RP[i] = rpb[i];
;     __syncthreads();
;     const int lane = F.lane, n = lane & 15, q4 = lane >> 4;
;     const int vcu = (F.G % 8 == 0) ? (F.bid % 8) * (F.G / 8) + F.bid / 8 : F.bid;
;     for (int br = vcu; br < MB * 256; br += F.G) {
;         const int b = br >> 8, r = br & 255;
;         const int rs = min(max(r - 4, 0), 248);
; #pragma unroll 1
;         for (int it = 0; it < 8; ++it) {
;             const int hj = it * 8 + F.wave, h = hj >> 2, j = hj & 3;
;             const int c0 = (j == 0) ? 0 : (j == 1) ? 8 : (j == 2) ? 24 : 32;
;             const int qcol = 16 * j + n, cs = min(max(qcol - 8, 0), 48);
;             const size_t tokq = (size_t)b * SEQL + r * 64 + qcol;
;             bf16x8 qf[2];
; #pragma unroll
;             for (int ks = 0; ks < 2; ++ks) qf[ks] = *(const bf16x8*)(QH + (((size_t)h * 2 + ks) * MTOK + tokq) * 32 + q4 * 8);
;             f32x4 acc[16];
; #pragma unroll
;             for (int blk = 0; blk < 16; ++blk) { const int i = blk >> 1, hf = blk & 1;
;                 const size_t tokk = (size_t)b * SEQL + (rs + i) * 64 + c0 + 8 * (n >> 2) + 4 * hf + (n & 3);
;                 const bf16* kp = KH + ((size_t)h * 2 * MTOK + tokk) * 32 + q4 * 8; const bf16x8 k0 = *(const bf16x8*)kp, k1 = *(const bf16x8*)(kp + (size_t)MTOK * 32);
;                 f32x4 a = (f32x4){0.f, 0.f, 0.f, 0.f};
;                 a = __builtin_amdgcn_mfma_f32_16x16x32_bf16(k0, qf[0], a, 0, 0, 0);
;                 a = __builtin_amdgcn_mfma_f32_16x16x32_bf16(k1, qf[1], a, 0, 0, 0);
;                 acc[blk] = a; }
;             float mx = -3.0e38f;
;             int cofs[8]; bool okk[8];
; #pragma unroll
;             for (int k8 = 0; k8 < 8; ++k8) { const int kc = c0 + 8 * q4 + 4 * (k8 >> 2) + (k8 & 3); okk[k8] = (kc >= cs) && (kc < cs + 16); cofs[k8] = min(max(kc - qcol + 15, 0), 30); }
.LBB0_899:
	s_cmp_lt_i32 s72, 10
	s_cselect_b64 s[4:5], -1, 0
	s_and_b64 s[36:37], s[4:5], s[0:1]
	s_andn2_b64 vcc, exec, s[36:37]
	s_cbranch_vccnz .LBB0_913
	v_lshlrev_b32_e32 v4, 2, v221
	v_add_u32_e32 v3, 0, v4
	s_waitcnt lgkmcnt(0)
	v_add_u32_e32 v6, 0x1000, v4
	v_add_u32_e32 v7, 0x2000, v4
	v_add_u32_e32 v8, 0x3000, v4
	v_add_u32_e32 v9, 0x4000, v4
	v_add_u32_e32 v26, 0x5000, v4
	v_add_u32_e32 v27, 0x6000, v4
	v_add_u32_e32 v28, 0x7000, v4
	global_load_dword v10, v4, s[24:25]
	global_load_dword v11, v4, s[24:25] offset:2048
	global_load_dword v12, v6, s[24:25]
	global_load_dword v13, v6, s[24:25] offset:2048
	global_load_dword v14, v7, s[24:25]
	global_load_dword v15, v7, s[24:25] offset:2048
	global_load_dword v16, v8, s[24:25]
	global_load_dword v17, v8, s[24:25] offset:2048
	global_load_dword v18, v9, s[24:25]
	global_load_dword v19, v9, s[24:25] offset:2048
	global_load_dword v20, v26, s[24:25]
	global_load_dword v21, v26, s[24:25] offset:2048
	global_load_dword v22, v27, s[24:25]
	global_load_dword v23, v27, s[24:25] offset:2048
	v_cmp_gt_u32_e32 vcc, 0x110, v221
	s_nop 1
	s_and_saveexec_b64 s[0:1], vcc
	global_load_dword v24, v28, s[24:25]
	s_mov_b64 exec, s[0:1]
	s_waitcnt vmcnt(0)
	ds_write_b32 v3, v10
	ds_write_b32 v3, v11 offset:2048
	ds_write_b32 v3, v12 offset:4096
	ds_write_b32 v3, v13 offset:6144
	ds_write_b32 v3, v14 offset:8192
	ds_write_b32 v3, v15 offset:10240
	ds_write_b32 v3, v16 offset:12288
	ds_write_b32 v3, v17 offset:14336
	ds_write_b32 v3, v18 offset:16384
	ds_write_b32 v3, v19 offset:18432
	ds_write_b32 v3, v20 offset:20480
	ds_write_b32 v3, v21 offset:22528
	ds_write_b32 v3, v22 offset:24576
	ds_write_b32 v3, v23 offset:26624
	s_and_saveexec_b64 s[0:1], vcc
	ds_write_b32 v3, v24 offset:28672
	s_mov_b64 exec, s[0:1]
	s_ashr_i32 s1, s2, 31
	s_lshr_b32 s1, s1, 29
	s_add_i32 s1, s2, s1
	s_ashr_i32 s3, s1, 3
	s_and_b32 s1, s1, -8
	s_sub_i32 s1, s2, s1
	s_ashr_i32 s4, s74, 3
	s_mul_i32 s1, s4, s1
	s_and_b32 s0, s74, 7
	s_add_i32 s1, s1, s3
	s_cmp_eq_u32 s0, 0
	s_cselect_b32 s3, s1, s2
	s_mov_b32 s47, 0
	s_cmpk_lt_i32 s3, 0x200
	s_waitcnt lgkmcnt(0)
	s_barrier
	s_cbranch_scc0 .LBB0_912
	v_mbcnt_lo_u32_b32 v3, -1, 0
	v_readlane_b32 s0, v248, 14
	v_mbcnt_hi_u32_b32 v3, -1, v3
	s_bfe_u32 s6, s0, 0x20006
	v_and_b32_e32 v5, 64, v3
	s_lshl_b32 s8, s6, 4
	v_xor_b32_e32 v4, 16, v3
	v_add_u32_e32 v5, 64, v5
	s_cmp_eq_u32 s6, 2
	v_cmp_lt_i32_e32 vcc, v4, v5
	v_and_b32_e32 v0, 15, v221
	v_lshrrev_b32_e32 v72, 4, v220
	s_cselect_b32 s7, 24, 32
	v_cndmask_b32_e32 v4, v3, v4, vcc
	s_lshr_b32 s46, s0, 8
	v_or_b32_e32 v1, s8, v0
	v_lshlrev_b32_e32 v48, 3, v72
	v_lshlrev_b32_e32 v73, 2, v4
	v_xor_b32_e32 v4, 32, v3
	s_lshl_b64 s[0:1], s[46:47], 22
	v_sub_u32_e64 v1, v1, 8 clamp
	v_cmp_lt_i32_e32 vcc, v4, v5
	v_lshl_or_b32 v52, v0, 4, s0
	v_mov_b32_e32 v53, s1
	v_add_u32_e32 v75, s8, v0
	v_sub_u32_e32 v0, v48, v0
	s_mul_i32 s1, s46, 0x744
	v_min_u32_e32 v49, 48, v1
	v_mov_b32_e32 v51, 0
	v_lshlrev_b32_e32 v1, 1, v221
	v_and_b32_e32 v2, 3, v221
	v_cndmask_b32_e32 v3, v3, v4, vcc
	v_lshl_or_b32 v50, s46, 7, v48
	s_mov_b64 s[4:5], 0x8000040
	v_subrev_u32_e32 v76, s8, v0
	s_add_i32 s33, s1, 0
	v_add_u32_e32 v57, 16, v49
	v_lshlrev_b32_e32 v74, 2, v3
	v_lshl_add_u64 v[54:55], v[50:51], 0, s[4:5]
	s_addk_i32 s33, 0x364
	v_and_or_b32 v56, v1, 24, v2
	s_cmp_eq_u32 s6, 0
	s_cselect_b32 s98, 0, s7
	s_cmp_eq_u32 s6, 1
	s_cselect_b32 s98, 8, s98
	s_lshl_b32 s98, s98, 3
	v_and_b32_e32 v252, 15, v221
	v_lshrrev_b32_e32 v253, 2, v252
	v_and_b32_e32 v254, 3, v252
	v_lshlrev_b32_e32 v249, 10, v72
	v_lshl_or_b32 v250, v254, 4, v249
	v_lshl_or_b32 v249, v253, 6, v250
	v_add_u32_e32 v249, s98, v249
	v_and_b32_e32 v254, 1, v253
	v_lshl_or_b32 v250, v254, 9, v250
	v_lshrrev_b32_e32 v254, 3, v252
	v_lshl_add_u32 v254, s6, 1, v254
	v_lshl_or_b32 v250, v254, 6, v250
	v_mov_b32_e32 v58, s0
	s_mov_b64 s[90:91], -1
	s_mov_b64 s[92:93], -1
	s_mov_b64 s[98:99], 0
	s_cmp_eq_u32 s6, 0
	s_cselect_b32 s90, 0x0fff0fff, s90
	s_cselect_b32 s91, 0x0fff0fff, s91
	s_cselect_b32 s93, 0x0000ffff, s93
	s_cselect_b32 s99, 0xffff0000, s99
	s_cmp_eq_u32 s6, 3
	s_cselect_b32 s90, 0xfff0fff0, s90
	s_cselect_b32 s91, 0xfff0fff0, s91
	s_cselect_b32 s92, 0xffff0000, s92
	s_cselect_b32 s98, 0x0000ffff, s98
	v_mov_b32_e32 v59, v53
	v_add_u32_e32 v77, 1, v76
	v_add_u32_e32 v78, 2, v76
	v_add_u32_e32 v79, 3, v76
	v_add_u32_e32 v80, 4, v76
	v_add_u32_e32 v81, 5, v76
	v_add_u32_e32 v82, 6, v76
	v_add_u32_e32 v83, 7, v76
	s_movk_i32 s52, 0x7c
	s_brev_b32 s53, 8
	s_mov_b32 s54, 0x10200000
	s_mov_b32 s55, 0x10001000
	s_mov_b32 s56, 0x10201000
	s_mov_b32 s57, 0x10002000
	s_mov_b32 s58, 0x10202000
	s_mov_b32 s59, 0x10003000
	s_mov_b32 s60, 0x10203000
	s_mov_b32 s61, 0x10004000
	s_mov_b32 s62, 0x10204000
	s_mov_b32 s63, 0x10005000
	s_mov_b32 s64, 0x10205000
	s_mov_b32 s65, 0x10006000
	s_mov_b32 s66, 0x10206000
	s_mov_b32 s67, 0x10007000
	s_mov_b32 s76, 0x10207000
	s_mov_b32 s77, 0xff61b1e6
	v_mov_b32_e32 v84, 0xff61b1e6
	s_brev_b32 s78, 40
	s_mov_b32 s79, 0x14002000
	s_mov_b32 s80, 0x14004000
	s_mov_b32 s81, 0x14006000
	s_mov_b32 s82, 0x14008000
	s_mov_b32 s83, 0x1400a000
	s_mov_b32 s84, 0x1400c000
	s_mov_b32 s85, 0x1400e000
	s_mov_b64 s[48:49], 0x800000
	s_mov_b64 s[50:51], 0x100
	s_mov_b32 s86, s3
	s_branch .LBB0_905

; __device__ __forceinline__ void na_phase(const Frame& F, const bf16* QH, const bf16* VB, const float* rpb, bf16* U) {
;     ...
;             const int qcol = 16 * j + n, cs = min(max(qcol - 8, 0), 48);
;             const size_t tokq = (size_t)b * SEQL + r * 64 + qcol;
;             bf16x8 qf[2];
; #pragma unroll
;             for (int ks = 0; ks < 2; ++ks) qf[ks] = *(const bf16x8*)(QH + (((size_t)h * 2 + ks) * MTOK + tokq) * 32 + q4 * 8);
;             f32x4 acc[16];
; #pragma unroll
;             for (int blk = 0; blk < 16; ++blk) { const int i = blk >> 1, hf = blk & 1;
;                 const size_t tokk = (size_t)b * SEQL + (rs + i) * 64 + c0 + 8 * (n >> 2) + 4 * hf + (n & 3);
;                 const bf16* kp = KH + ((size_t)h * 2 * MTOK + tokk) * 32 + q4 * 8; const bf16x8 k0 = *(const bf16x8*)kp, k1 = *(const bf16x8*)(kp + (size_t)MTOK * 32);
;                 f32x4 a = (f32x4){0.f, 0.f, 0.f, 0.f};
;                 a = __builtin_amdgcn_mfma_f32_16x16x32_bf16(k0, qf[0], a, 0, 0, 0);
;                 a = __builtin_amdgcn_mfma_f32_16x16x32_bf16(k1, qf[1], a, 0, 0, 0);
;                 acc[blk] = a; }
.LBB0_906:
	v_lshl_add_u64 v[0:1], s[70:71], 0, v[68:69]
	v_add_co_u32_e32 v2, vcc, 0xc000000, v0
	v_mov_b32_e32 v50, 0
	s_nop 0
	v_addc_co_u32_e32 v3, vcc, 0, v1, vcc
	v_add_co_u32_e32 v4, vcc, 0xc200000, v0
	v_lshl_add_u64 v[68:69], v[68:69], 0, s[48:49]
	s_nop 0
	v_addc_co_u32_e32 v5, vcc, 0, v1, vcc
	global_load_dwordx4 v[0:3], v[2:3], off
	s_nop 0
	global_load_dwordx4 v[86:89], v[4:5], off
	v_lshl_add_u64 v[4:5], v[64:65], 0, 0
	v_lshlrev_b64 v[4:5], 6, v[4:5]
	v_lshl_add_u64 v[4:5], v[70:71], 0, v[4:5]
	v_lshl_add_u64 v[4:5], s[70:71], 0, v[4:5]
	v_add_co_u32_e32 v8, vcc, 0x10000000, v4
	v_lshl_add_u64 v[70:71], v[70:71], 0, s[48:49]
	s_nop 0
	v_addc_co_u32_e32 v9, vcc, 0, v5, vcc
	v_add_co_u32_e32 v12, vcc, 0x10200000, v4
	s_nop 1
	v_addc_co_u32_e32 v13, vcc, 0, v5, vcc
	v_lshl_add_u64 v[4:5], v[66:67], 0, v[50:51]
	v_lshl_add_u64 v[114:115], s[70:71], 0, v[4:5]
	v_add_co_u32_e32 v106, vcc, s61, v114
	v_add_u32_e32 v50, s46, v48
	s_nop 0
	v_addc_co_u32_e32 v107, vcc, 0, v115, vcc
	v_add_co_u32_e32 v16, vcc, s53, v114
	s_mov_b64 exec, s[90:91]
	global_load_dwordx4 v[4:7], v[106:107], off offset:-4096
	s_mov_b64 exec, -1
	s_nop 0
	s_mov_b64 exec, s[90:91]
	global_load_dwordx4 v[8:11], v[8:9], off
	s_mov_b64 exec, -1
	s_nop 0
	s_mov_b64 exec, s[90:91]
	global_load_dwordx4 v[12:15], v[12:13], off
	s_mov_b64 exec, -1
	v_addc_co_u32_e32 v17, vcc, 0, v115, vcc
	v_add_co_u32_e32 v28, vcc, s54, v114
	s_mov_b64 s[0:1], vcc
	v_add_co_u32_e32 v20, vcc, s55, v114
	s_mov_b64 exec, s[90:91]
	global_load_dwordx4 v[16:19], v[16:17], off offset:512
	s_mov_b64 exec, -1
	s_nop 0
	v_addc_co_u32_e32 v21, vcc, 0, v115, vcc
	s_mov_b64 exec, s[90:91]
	global_load_dwordx4 v[20:23], v[20:21], off offset:512
	s_mov_b64 exec, -1
	s_nop 0
	s_mov_b64 exec, s[90:91]
	global_load_dwordx4 v[24:27], v[106:107], off
	s_mov_b64 exec, -1
	v_addc_co_u32_e64 v29, vcc, 0, v115, s[0:1]
	v_add_co_u32_e32 v36, vcc, s57, v114
	s_mov_b64 exec, s[90:91]
	global_load_dwordx4 v[28:31], v[28:29], off offset:512
	s_mov_b64 exec, -1
	s_nop 0
	v_addc_co_u32_e32 v37, vcc, 0, v115, vcc
	v_add_co_u32_e32 v38, vcc, s56, v114
	s_mov_b64 exec, s[90:91]
	global_load_dwordx4 v[32:35], v[36:37], off offset:-4096
	s_mov_b64 exec, -1
	s_nop 0
	v_addc_co_u32_e32 v39, vcc, 0, v115, vcc
	v_add_co_u32_e32 v40, vcc, s58, v114
	v_cmp_lt_u32_e64 s[0:1], v50, v57
	s_nop 0
	v_addc_co_u32_e32 v41, vcc, 0, v115, vcc
	v_add_co_u32_e32 v108, vcc, s62, v114
	v_lshl_add_u64 v[66:67], v[66:67], 0, s[48:49]
	s_nop 0
	v_addc_co_u32_e32 v109, vcc, 0, v115, vcc
	s_waitcnt vmcnt(7)
	v_mfma_f32_16x16x32_bf16 v[4:7], v[4:7], v[0:3], 0
	s_waitcnt vmcnt(6)
	v_mfma_f32_16x16x32_bf16 v[8:11], v[8:11], v[0:3], 0
	s_waitcnt vmcnt(5)
	v_mfma_f32_16x16x32_bf16 v[90:93], v[12:15], v[86:89], v[8:11]
	s_waitcnt vmcnt(3)
	v_mfma_f32_16x16x32_bf16 v[12:15], v[20:23], v[0:3], 0
	s_nop 3
	s_mov_b64 exec, s[90:91]
	global_load_dwordx4 v[8:11], v[38:39], off offset:512
	s_mov_b64 exec, -1
	s_mov_b64 exec, s[90:91]
	global_load_dwordx4 v[20:23], v[36:37], off
	s_mov_b64 exec, -1
	s_nop 0
	s_mov_b64 exec, s[90:91]
	global_load_dwordx4 v[36:39], v[36:37], off offset:512
	s_mov_b64 exec, -1
	s_nop 1
	v_mfma_f32_16x16x32_bf16 v[16:19], v[16:19], v[0:3], 0
	s_waitcnt vmcnt(4)
	v_mfma_f32_16x16x32_bf16 v[94:97], v[28:31], v[86:89], v[16:19]
	s_nop 5
	s_mov_b64 exec, s[90:91]
	global_load_dwordx4 v[16:19], v[40:41], off offset:-4096
	s_mov_b64 exec, -1
	s_waitcnt vmcnt(4)
	v_mfma_f32_16x16x32_bf16 v[32:35], v[32:35], v[0:3], 0
	s_waitcnt vmcnt(3)
	v_mfma_f32_16x16x32_bf16 v[98:101], v[8:11], v[86:89], v[12:15]
	s_nop 2
	v_add_co_u32_e32 v12, vcc, s59, v114
	s_waitcnt vmcnt(1)
	v_mfma_f32_16x16x32_bf16 v[28:31], v[36:39], v[0:3], 0
	s_mov_b64 exec, s[90:91]
	global_load_dwordx4 v[36:39], v[40:41], off
	s_mov_b64 exec, -1
	s_nop 0
	s_mov_b64 exec, s[90:91]
	global_load_dwordx4 v[40:43], v[40:41], off offset:512
	s_mov_b64 exec, -1
	v_addc_co_u32_e32 v13, vcc, 0, v115, vcc
	s_mov_b64 exec, s[90:91]
	global_load_dwordx4 v[8:11], v[108:109], off offset:-4096
	s_mov_b64 exec, -1
	s_nop 1
	v_mfma_f32_16x16x32_bf16 v[20:23], v[20:23], v[0:3], 0
	s_mov_b64 exec, s[90:91]
	global_load_dwordx4 v[12:15], v[12:13], off offset:512
	s_mov_b64 exec, -1
	s_waitcnt vmcnt(4)
	v_mfma_f32_16x16x32_bf16 v[102:105], v[16:19], v[86:89], v[32:35]
	s_mov_b64 exec, s[90:91]
	global_load_dwordx4 v[16:19], v[106:107], off offset:512
	s_mov_b64 exec, -1
	s_waitcnt vmcnt(4)
	v_mfma_f32_16x16x32_bf16 v[44:47], v[36:39], v[86:89], v[20:23]
	s_nop 2
	v_add_co_u32_e32 v20, vcc, s60, v114
	s_nop 1
	v_addc_co_u32_e32 v21, vcc, 0, v115, vcc
	s_waitcnt vmcnt(2)
	v_mfma_f32_16x16x32_bf16 v[36:39], v[8:11], v[86:89], v[4:7]
	s_nop 2
	s_mov_b64 exec, s[90:91]
	global_load_dwordx4 v[4:7], v[20:21], off offset:512
	s_mov_b64 exec, -1
	s_waitcnt vmcnt(2)
	v_mfma_f32_16x16x32_bf16 v[8:11], v[12:15], v[0:3], 0
	v_mfma_f32_16x16x32_bf16 v[40:43], v[40:43], v[86:89], v[28:31]
	s_nop 2
	v_add_co_u32_e32 v28, vcc, s65, v114
	s_waitcnt vmcnt(0)
	v_mfma_f32_16x16x32_bf16 v[32:35], v[4:7], v[86:89], v[8:11]
	s_nop 2
	s_mov_b64 exec, s[90:91]
	global_load_dwordx4 v[8:11], v[108:109], off
	s_mov_b64 exec, -1
	s_mov_b64 exec, s[90:91]
	global_load_dwordx4 v[12:15], v[108:109], off offset:512
	s_mov_b64 exec, -1
	v_addc_co_u32_e32 v29, vcc, 0, v115, vcc
	v_mfma_f32_16x16x32_bf16 v[4:7], v[24:27], v[0:3], 0
	v_add_co_u32_e32 v110, vcc, s66, v114
	s_mov_b64 exec, s[90:91]
	global_load_dwordx4 v[106:109], v[28:29], off offset:512
	s_mov_b64 exec, -1
	s_waitcnt vmcnt(2)
; #define LAS __attribute__((address_space(3)))
; __device__ __forceinline__ void na_phase(const Frame& F, const bf16* QH, const bf16* VB, const float* rpb, bf16* U) {
;     ...
;             for (int blk = 0; blk < 16; ++blk) { const int i = blk >> 1, hf = blk & 1;
;                 const size_t tokk = (size_t)b * SEQL + (rs + i) * 64 + c0 + 8 * (n >> 2) + 4 * hf + (n & 3);
;                 const bf16* kp = KH + ((size_t)h * 2 * MTOK + tokk) * 32 + q4 * 8; const bf16x8 k0 = *(const bf16x8*)kp, k1 = *(const bf16x8*)(kp + (size_t)MTOK * 32);
;                 f32x4 a = (f32x4){0.f, 0.f, 0.f, 0.f};
;                 a = __builtin_amdgcn_mfma_f32_16x16x32_bf16(k0, qf[0], a, 0, 0, 0);
;                 a = __builtin_amdgcn_mfma_f32_16x16x32_bf16(k1, qf[1], a, 0, 0, 0);
;                 acc[blk] = a; }
;             float mx = -3.0e38f;
;             int cofs[8]; bool okk[8];
; #pragma unroll
;             for (int k8 = 0; k8 < 8; ++k8) { const int kc = c0 + 8 * q4 + 4 * (k8 >> 2) + (k8 & 3); okk[k8] = (kc >= cs) && (kc < cs + 16); cofs[k8] = min(max(kc - qcol + 15, 0), 30); }
; #pragma unroll
;             for (int i = 0; i < 8; ++i) { const LAS float* rprow = RP + (h * 15 + (rs + i - r + 7)) * 31;
; #pragma unroll
;                 for (int k8 = 0; k8 < 8; ++k8) { const int blk = 2 * i + (k8 >> 2), e = k8 & 3;
;                     const float bia = rprow[cofs[k8]];
;                     const float sb = acc[blk][e] * 0.125f + bia; const float s = okk[k8] ? sb : -3.0e38f;
;                     acc[blk][e] = s; mx = fmaxf(mx, s); } }
	v_mfma_f32_16x16x32_bf16 v[20:23], v[8:11], v[86:89], v[4:7]
	s_nop 3
	s_mov_b64 exec, s[90:91]
	global_load_dwordx4 v[4:7], v[28:29], off offset:-4096
	s_mov_b64 exec, -1
	v_addc_co_u32_e32 v111, vcc, 0, v115, vcc
	v_mfma_f32_16x16x32_bf16 v[8:11], v[16:19], v[0:3], 0
	s_mov_b64 exec, s[90:91]
	global_load_dwordx4 v[16:19], v[110:111], off offset:-4096
	s_mov_b64 exec, -1
	s_waitcnt vmcnt(3)
	v_mfma_f32_16x16x32_bf16 v[24:27], v[12:15], v[86:89], v[8:11]
	v_add_co_u32_e32 v12, vcc, s63, v114
	s_nop 1
	v_addc_co_u32_e32 v13, vcc, 0, v115, vcc
	s_mov_b64 exec, s[90:91]
	global_load_dwordx4 v[12:15], v[12:13], off offset:512
	s_mov_b64 exec, -1
	v_add_co_u32_e32 v112, vcc, s64, v114
	s_mov_b64 exec, s[90:91]
	global_load_dwordx4 v[8:11], v[28:29], off
	s_mov_b64 exec, -1
	s_nop 0
	v_addc_co_u32_e32 v113, vcc, 0, v115, vcc
	v_add_co_u32_e32 v116, vcc, s67, v114
	s_waitcnt vmcnt(3)
	v_mfma_f32_16x16x32_bf16 v[4:7], v[4:7], v[0:3], 0
	v_addc_co_u32_e32 v117, vcc, 0, v115, vcc
	v_add_co_u32_e32 v114, vcc, s76, v114
	s_waitcnt vmcnt(2)
	v_mfma_f32_16x16x32_bf16 v[28:31], v[16:19], v[86:89], v[4:7]
	v_addc_co_u32_e32 v115, vcc, 0, v115, vcc
	v_cmp_ge_u32_e32 vcc, v50, v49
	s_nop 1
	s_mov_b64 exec, s[90:91]
	global_load_dwordx4 v[4:7], v[112:113], off offset:512
	s_mov_b64 exec, -1
	s_waitcnt vmcnt(2)
	v_mfma_f32_16x16x32_bf16 v[12:15], v[12:15], v[0:3], 0
	s_and_b64 vcc, vcc, s[0:1]
	s_waitcnt vmcnt(0)
	v_mfma_f32_16x16x32_bf16 v[16:19], v[4:7], v[86:89], v[12:15]
	v_mfma_f32_16x16x32_bf16 v[4:7], v[8:11], v[0:3], 0
	s_mov_b64 exec, s[90:91]
	global_load_dwordx4 v[8:11], v[110:111], off
	s_mov_b64 exec, -1
	s_nop 0
	s_mov_b64 exec, s[90:91]
	global_load_dwordx4 v[110:113], v[110:111], off offset:512
	s_mov_b64 exec, -1
	s_waitcnt vmcnt(1)
	v_mfma_f32_16x16x32_bf16 v[12:15], v[8:11], v[86:89], v[4:7]
	s_nop 2
	s_mov_b64 exec, s[90:91]
	global_load_dwordx4 v[4:7], v[116:117], off
	s_mov_b64 exec, -1
	s_nop 1
	v_mfma_f32_16x16x32_bf16 v[8:11], v[106:109], v[0:3], 0
	s_mov_b64 exec, s[90:91]
	global_load_dwordx4 v[106:109], v[114:115], off
	s_mov_b64 exec, -1
	s_waitcnt vmcnt(2)
	v_mfma_f32_16x16x32_bf16 v[8:11], v[110:113], v[86:89], v[8:11]
	s_mov_b64 exec, s[90:91]
	global_load_dwordx4 v[110:113], v[116:117], off offset:512
	s_mov_b64 exec, -1
	s_nop 0
	s_mov_b64 exec, s[90:91]
	global_load_dwordx4 v[114:117], v[114:115], off offset:512
	s_mov_b64 exec, -1
	s_waitcnt vmcnt(3)
	v_mfma_f32_16x16x32_bf16 v[4:7], v[4:7], v[0:3], 0
	s_waitcnt vmcnt(1)
	v_mfma_f32_16x16x32_bf16 v[0:3], v[110:113], v[0:3], 0
	v_add_u32_e32 v110, s87, v85
	s_addk_i32 s87, 0xe88
	v_mfma_f32_16x16x32_bf16 v[4:7], v[106:109], v[86:89], v[4:7]
	s_waitcnt vmcnt(0)
	v_mfma_f32_16x16x32_bf16 v[0:3], v[114:117], v[86:89], v[0:3]
	v_or_b32_e32 v86, 1, v50
	v_cmp_ge_u32_e64 s[4:5], v86, v49
	v_cmp_lt_u32_e64 s[8:9], v86, v57
	v_or_b32_e32 v86, 2, v50
	v_cmp_ge_u32_e64 s[10:11], v86, v49
	v_cmp_lt_u32_e64 s[12:13], v86, v57
	v_or_b32_e32 v86, 3, v50
	v_cmp_ge_u32_e64 s[14:15], v86, v49
	v_cmp_lt_u32_e64 s[16:17], v86, v57
	v_or_b32_e32 v86, 4, v50
	v_cmp_ge_u32_e64 s[18:19], v86, v49
	v_cmp_lt_u32_e64 s[20:21], v86, v57
	v_or_b32_e32 v86, 5, v50
	v_cmp_ge_u32_e64 s[22:23], v86, v49
	v_cmp_lt_u32_e64 s[24:25], v86, v57
	v_or_b32_e32 v86, 6, v50
	v_cmp_ge_u32_e64 s[26:27], v86, v49
	v_cmp_lt_u32_e64 s[28:29], v86, v57
	v_add_u32_e32 v86, s46, v76
	v_add_u32_e32 v88, s46, v77
	v_max_i32_e32 v86, -15, v86
	v_max_i32_e32 v88, -15, v88
	v_add_u32_e32 v86, 15, v86
	v_add_u32_e32 v88, 15, v88
	v_min_u32_e32 v86, 30, v86
	v_min_u32_e32 v88, 30, v88
	v_lshl_add_u32 v112, v86, 2, v110
	v_lshl_add_u32 v113, v88, 2, v110
	ds_read2_b32 v[86:87], v112 offset1:31
	ds_read2_b32 v[88:89], v113 offset1:31
	v_or_b32_e32 v50, 7, v50
	v_cmp_ge_u32_e64 s[30:31], v50, v49
	v_cmp_lt_u32_e64 s[34:35], v50, v57
	s_waitcnt lgkmcnt(1)
	v_fmamk_f32 v50, v90, 0x3e000000, v86
	s_waitcnt lgkmcnt(0)
	v_fmamk_f32 v86, v91, 0x3e000000, v88
	s_and_b64 s[0:1], s[4:5], s[8:9]
	v_cndmask_b32_e64 v114, v84, v86, s[0:1]
	v_add_u32_e32 v86, s46, v78
	v_max_i32_e32 v86, -15, v86
	v_add_u32_e32 v86, 15, v86
	v_min_u32_e32 v86, 30, v86
	v_lshl_add_u32 v115, v86, 2, v110
	v_add_u32_e32 v86, s46, v79
	v_max_i32_e32 v86, -15, v86
	v_add_u32_e32 v86, 15, v86
	v_min_u32_e32 v86, 30, v86
	ds_read2_b32 v[90:91], v115 offset1:31
	v_lshl_add_u32 v116, v86, 2, v110
	ds_read2_b32 v[106:107], v116 offset1:31
	s_and_b64 s[4:5], s[10:11], s[12:13]
	s_and_b64 s[8:9], s[14:15], s[16:17]
	s_waitcnt lgkmcnt(1)
	v_fmamk_f32 v88, v92, 0x3e000000, v90
	v_cndmask_b32_e64 v117, v84, v88, s[4:5]
	s_waitcnt lgkmcnt(0)
	v_fmamk_f32 v88, v93, 0x3e000000, v106
	v_cndmask_b32_e64 v106, v84, v88, s[8:9]
	v_add_u32_e32 v88, s46, v80
	v_max_i32_e32 v88, -15, v88
	v_add_u32_e32 v88, 15, v88
	v_min_u32_e32 v88, 30, v88
	v_lshl_add_u32 v118, v88, 2, v110
	v_add_u32_e32 v88, s46, v81
	v_max_i32_e32 v88, -15, v88
	v_add_u32_e32 v88, 15, v88
	v_min_u32_e32 v88, 30, v88
	ds_read2_b32 v[92:93], v118 offset1:31
	v_lshl_add_u32 v119, v88, 2, v110
	ds_read2_b32 v[108:109], v119 offset1:31
	s_and_b64 s[10:11], s[18:19], s[20:21]
	s_and_b64 s[12:13], s[22:23], s[24:25]
	s_waitcnt lgkmcnt(1)
	v_fmamk_f32 v88, v94, 0x3e000000, v92
	v_cndmask_b32_e64 v120, v84, v88, s[10:11]
	s_waitcnt lgkmcnt(0)
	v_fmamk_f32 v88, v95, 0x3e000000, v108
	v_cndmask_b32_e64 v108, v84, v88, s[12:13]
	v_add_u32_e32 v88, s46, v82
	v_max_i32_e32 v88, -15, v88
	v_add_u32_e32 v88, 15, v88
	v_min_u32_e32 v88, 30, v88
	v_lshl_add_u32 v121, v88, 2, v110
	v_add_u32_e32 v88, s46, v83
	v_max_i32_e32 v88, -15, v88
	v_add_u32_e32 v88, 15, v88
	v_min_u32_e32 v88, 30, v88
	ds_read2_b32 v[94:95], v121 offset1:31
	v_lshl_add_u32 v122, v88, 2, v110
	ds_read2_b32 v[110:111], v122 offset1:31
	v_cndmask_b32_e32 v50, v84, v50, vcc
	v_max3_f32 v86, v50, s77, v114
	s_waitcnt lgkmcnt(1)
; #define LAS __attribute__((address_space(3)))
; __device__ __forceinline__ void na_phase(const Frame& F, const bf16* QH, const bf16* VB, const float* rpb, bf16* U) {
;     ...
;             for (int i = 0; i < 8; ++i) { const LAS float* rprow = RP + (h * 15 + (rs + i - r + 7)) * 31;
; #pragma unroll
;                 for (int k8 = 0; k8 < 8; ++k8) { const int blk = 2 * i + (k8 >> 2), e = k8 & 3;
;                     const float bia = rprow[cofs[k8]];
;                     const float sb = acc[blk][e] * 0.125f + bia; const float s = okk[k8] ? sb : -3.0e38f;
;                     acc[blk][e] = s; mx = fmaxf(mx, s); } }
	v_fmamk_f32 v88, v96, 0x3e000000, v94
	s_and_b64 s[14:15], s[26:27], s[28:29]
	v_max3_f32 v86, v86, v117, v106
	v_cndmask_b32_e64 v96, v84, v88, s[14:15]
	s_waitcnt lgkmcnt(0)
	v_fmamk_f32 v88, v97, 0x3e000000, v110
	s_and_b64 s[16:17], s[30:31], s[34:35]
	v_max3_f32 v86, v86, v120, v108
	v_cndmask_b32_e64 v97, v84, v88, s[16:17]
	v_fmac_f32_e32 v87, 0x3e000000, v102
	v_fmac_f32_e32 v89, 0x3e000000, v103
	v_max3_f32 v86, v86, v96, v97
	v_cndmask_b32_e32 v102, v84, v87, vcc
	v_cndmask_b32_e64 v103, v84, v89, s[0:1]
	v_fmac_f32_e32 v91, 0x3e000000, v104
	v_fmac_f32_e32 v107, 0x3e000000, v105
	v_max3_f32 v86, v86, v102, v103
	v_cndmask_b32_e64 v104, v84, v91, s[4:5]
	v_cndmask_b32_e64 v105, v84, v107, s[8:9]
	v_fmac_f32_e32 v93, 0x3e000000, v98
	v_fmac_f32_e32 v109, 0x3e000000, v99
	v_max3_f32 v86, v86, v104, v105
	v_cndmask_b32_e64 v98, v84, v93, s[10:11]
	v_cndmask_b32_e64 v99, v84, v109, s[12:13]
	v_max3_f32 v90, v86, v98, v99
	ds_read2_b32 v[86:87], v112 offset0:62 offset1:93
	ds_read2_b32 v[88:89], v113 offset0:62 offset1:93
	v_fmac_f32_e32 v95, 0x3e000000, v100
	v_fmac_f32_e32 v111, 0x3e000000, v101
	v_cndmask_b32_e64 v100, v84, v95, s[14:15]
	v_cndmask_b32_e64 v101, v84, v111, s[16:17]
	s_waitcnt lgkmcnt(1)
	v_fmamk_f32 v44, v44, 0x3e000000, v86
	v_max3_f32 v92, v90, v100, v101
	v_cndmask_b32_e32 v86, v84, v44, vcc
	ds_read2_b32 v[90:91], v115 offset0:62 offset1:93
	s_waitcnt lgkmcnt(1)
	v_fmamk_f32 v44, v45, 0x3e000000, v88
	v_cndmask_b32_e64 v88, v84, v44, s[0:1]
	ds_read2_b32 v[44:45], v116 offset0:62 offset1:93
	v_max3_f32 v94, v92, v86, v88
	s_waitcnt lgkmcnt(1)
	v_fmamk_f32 v46, v46, 0x3e000000, v90
	ds_read2_b32 v[92:93], v118 offset0:62 offset1:93
	v_cndmask_b32_e64 v90, v84, v46, s[4:5]
	s_waitcnt lgkmcnt(1)
	v_fmamk_f32 v44, v47, 0x3e000000, v44
	ds_read2_b32 v[46:47], v119 offset0:62 offset1:93
	v_cndmask_b32_e64 v44, v84, v44, s[8:9]
	s_waitcnt lgkmcnt(1)
	v_fmamk_f32 v40, v40, 0x3e000000, v92
	v_max3_f32 v107, v94, v90, v44
	v_cndmask_b32_e64 v92, v84, v40, s[10:11]
	ds_read2_b32 v[94:95], v121 offset0:62 offset1:93
	s_waitcnt lgkmcnt(1)
	v_fmamk_f32 v46, v41, 0x3e000000, v46
	ds_read2_b32 v[40:41], v122 offset0:62 offset1:93
	v_cndmask_b32_e64 v46, v84, v46, s[12:13]
	v_fmac_f32_e32 v93, 0x3e000000, v32
	s_waitcnt lgkmcnt(1)
	v_fmamk_f32 v42, v42, 0x3e000000, v94
	v_fmac_f32_e32 v47, 0x3e000000, v33
	s_waitcnt lgkmcnt(0)
	v_fmamk_f32 v40, v43, 0x3e000000, v40
	ds_read2_b32 v[32:33], v112 offset0:124 offset1:155
	v_max3_f32 v107, v107, v92, v46
	v_cndmask_b32_e64 v42, v84, v42, s[14:15]
	v_cndmask_b32_e64 v43, v84, v40, s[16:17]
	v_fmac_f32_e32 v87, 0x3e000000, v36
	v_fmac_f32_e32 v89, 0x3e000000, v37
	v_fmac_f32_e32 v95, 0x3e000000, v34
	v_fmac_f32_e32 v41, 0x3e000000, v35
	ds_read2_b32 v[34:35], v113 offset0:124 offset1:155
	v_max3_f32 v40, v107, v42, v43
	v_cndmask_b32_e32 v87, v84, v87, vcc
	v_cndmask_b32_e64 v89, v84, v89, s[0:1]
	v_fmac_f32_e32 v91, 0x3e000000, v38
	v_fmac_f32_e32 v45, 0x3e000000, v39
	v_max3_f32 v36, v40, v87, v89
	v_cndmask_b32_e64 v91, v84, v91, s[4:5]
	v_cndmask_b32_e64 v45, v84, v45, s[8:9]
	v_max3_f32 v36, v36, v91, v45
	v_cndmask_b32_e64 v93, v84, v93, s[10:11]
	v_cndmask_b32_e64 v47, v84, v47, s[12:13]
	v_max3_f32 v36, v36, v93, v47
	v_cndmask_b32_e64 v94, v84, v95, s[14:15]
	v_cndmask_b32_e64 v95, v84, v41, s[16:17]
	s_waitcnt lgkmcnt(1)
	v_fmamk_f32 v20, v20, 0x3e000000, v32
	v_max3_f32 v38, v36, v94, v95
	v_cndmask_b32_e32 v107, v84, v20, vcc
	ds_read2_b32 v[36:37], v115 offset0:124 offset1:155
	s_waitcnt lgkmcnt(1)
	v_fmamk_f32 v20, v21, 0x3e000000, v34
	v_cndmask_b32_e64 v34, v84, v20, s[0:1]
	ds_read2_b32 v[20:21], v116 offset0:124 offset1:155
	v_max3_f32 v32, v38, v107, v34
	s_waitcnt lgkmcnt(1)
	v_fmamk_f32 v22, v22, 0x3e000000, v36
	ds_read2_b32 v[38:39], v118 offset0:124 offset1:155
	v_cndmask_b32_e64 v36, v84, v22, s[4:5]
	s_waitcnt lgkmcnt(1)
	v_fmamk_f32 v20, v23, 0x3e000000, v20
	ds_read2_b32 v[22:23], v119 offset0:124 offset1:155
	ds_read2_b32 v[40:41], v121 offset0:124 offset1:155
	s_waitcnt lgkmcnt(2)
	v_fmamk_f32 v24, v24, 0x3e000000, v38
	v_cndmask_b32_e64 v38, v84, v24, s[10:11]
	v_cndmask_b32_e64 v109, v84, v20, s[8:9]
	s_waitcnt lgkmcnt(1)
	v_fmamk_f32 v22, v25, 0x3e000000, v22
	ds_read2_b32 v[24:25], v122 offset0:124 offset1:155
	v_cndmask_b32_e64 v110, v84, v22, s[12:13]
	s_waitcnt lgkmcnt(1)
	v_fmamk_f32 v22, v26, 0x3e000000, v40
	v_max3_f32 v20, v32, v36, v109
	v_cndmask_b32_e64 v40, v84, v22, s[14:15]
	s_waitcnt lgkmcnt(0)
	v_fmamk_f32 v22, v27, 0x3e000000, v24
	v_max3_f32 v20, v20, v38, v110
	v_cndmask_b32_e64 v111, v84, v22, s[16:17]
	v_fmac_f32_e32 v33, 0x3e000000, v28
	v_fmac_f32_e32 v35, 0x3e000000, v29
	v_max3_f32 v20, v20, v40, v111
	v_cndmask_b32_e32 v123, v84, v33, vcc
	v_cndmask_b32_e64 v35, v84, v35, s[0:1]
	v_fmac_f32_e32 v37, 0x3e000000, v30
	v_fmac_f32_e32 v21, 0x3e000000, v31
	v_max3_f32 v20, v20, v123, v35
	v_cndmask_b32_e64 v37, v84, v37, s[4:5]
	v_cndmask_b32_e64 v124, v84, v21, s[8:9]
	v_fmac_f32_e32 v39, 0x3e000000, v16
	v_fmac_f32_e32 v23, 0x3e000000, v17
	v_max3_f32 v20, v20, v37, v124
	v_cndmask_b32_e64 v125, v84, v39, s[10:11]
	v_cndmask_b32_e64 v126, v84, v23, s[12:13]
	v_max3_f32 v16, v20, v125, v126
	ds_read2_b32 v[20:21], v112 offset0:186 offset1:217
	v_fmac_f32_e32 v41, 0x3e000000, v18
	v_fmac_f32_e32 v25, 0x3e000000, v19
	ds_read2_b32 v[18:19], v113 offset0:186 offset1:217
	v_cndmask_b32_e64 v127, v84, v41, s[14:15]
	v_cndmask_b32_e64 v112, v84, v25, s[16:17]
	s_waitcnt lgkmcnt(1)
	v_fmamk_f32 v12, v12, 0x3e000000, v20
	v_max3_f32 v26, v16, v127, v112
	v_cndmask_b32_e32 v16, v84, v12, vcc
	s_waitcnt lgkmcnt(0)
; #define LAS __attribute__((address_space(3)))
; __device__ __forceinline__ void na_phase(const Frame& F, const bf16* QH, const bf16* VB, const float* rpb, bf16* U) {
;     ...
;             for (int i = 0; i < 8; ++i) { const LAS float* rprow = RP + (h * 15 + (rs + i - r + 7)) * 31;
; #pragma unroll
;                 for (int k8 = 0; k8 < 8; ++k8) { const int blk = 2 * i + (k8 >> 2), e = k8 & 3;
;                     const float bia = rprow[cofs[k8]];
;                     const float sb = acc[blk][e] * 0.125f + bia; const float s = okk[k8] ? sb : -3.0e38f;
;                     acc[blk][e] = s; mx = fmaxf(mx, s); } }
;             mx = fmaxf(mx, __shfl_xor(mx, 16)); mx = fmaxf(mx, __shfl_xor(mx, 32));
;             float sum = 0.f;
; #pragma unroll
;             for (int blk = 0; blk < 16; ++blk)
; #pragma unroll
;                 for (int e = 0; e < 4; ++e) { const float p = __builtin_amdgcn_exp2f((acc[blk][e] - mx) * 1.44269504089f); acc[blk][e] = p; sum += p; }
	v_fmamk_f32 v12, v13, 0x3e000000, v18
	ds_read2_b32 v[22:23], v115 offset0:186 offset1:217
	v_cndmask_b32_e64 v17, v84, v12, s[0:1]
	ds_read2_b32 v[24:25], v116 offset0:186 offset1:217
	v_max3_f32 v12, v26, v16, v17
	ds_read2_b32 v[26:27], v118 offset0:186 offset1:217
	ds_read2_b32 v[28:29], v119 offset0:186 offset1:217
	ds_read2_b32 v[30:31], v121 offset0:186 offset1:217
	ds_read2_b32 v[32:33], v122 offset0:186 offset1:217
	s_waitcnt lgkmcnt(5)
	v_fmamk_f32 v13, v14, 0x3e000000, v22
	v_cndmask_b32_e64 v18, v84, v13, s[4:5]
	s_waitcnt lgkmcnt(4)
	v_fmamk_f32 v13, v15, 0x3e000000, v24
	s_waitcnt lgkmcnt(3)
	v_fmamk_f32 v8, v8, 0x3e000000, v26
	v_cndmask_b32_e64 v15, v84, v13, s[8:9]
	v_cndmask_b32_e64 v14, v84, v8, s[10:11]
	s_waitcnt lgkmcnt(2)
	v_fmamk_f32 v8, v9, 0x3e000000, v28
	v_max3_f32 v12, v12, v18, v15
	v_cndmask_b32_e64 v13, v84, v8, s[12:13]
	s_waitcnt lgkmcnt(1)
	v_fmamk_f32 v9, v10, 0x3e000000, v30
	v_max3_f32 v8, v12, v14, v13
	v_cndmask_b32_e64 v12, v84, v9, s[14:15]
	s_waitcnt lgkmcnt(0)
	v_fmamk_f32 v9, v11, 0x3e000000, v32
	v_cndmask_b32_e64 v11, v84, v9, s[16:17]
	v_fmac_f32_e32 v21, 0x3e000000, v4
	v_fmac_f32_e32 v19, 0x3e000000, v5
	v_max3_f32 v8, v8, v12, v11
	v_cndmask_b32_e32 v10, v84, v21, vcc
	v_cndmask_b32_e64 v9, v84, v19, s[0:1]
	v_fmac_f32_e32 v23, 0x3e000000, v6
	v_fmac_f32_e32 v25, 0x3e000000, v7
	v_max3_f32 v4, v8, v10, v9
	v_cndmask_b32_e64 v8, v84, v23, s[4:5]
	v_cndmask_b32_e64 v6, v84, v25, s[8:9]
	v_fmac_f32_e32 v27, 0x3e000000, v0
	v_fmac_f32_e32 v29, 0x3e000000, v1
	v_max3_f32 v7, v4, v8, v6
	v_cndmask_b32_e64 v5, v84, v27, s[10:11]
	v_cndmask_b32_e64 v4, v84, v29, s[12:13]
	v_fmac_f32_e32 v31, 0x3e000000, v2
	v_fmac_f32_e32 v33, 0x3e000000, v3
	v_max3_f32 v7, v7, v5, v4
	v_cndmask_b32_e64 v1, v84, v31, s[14:15]
	v_cndmask_b32_e64 v0, v84, v33, s[16:17]
	v_max3_f32 v2, v7, v1, v0
	ds_bpermute_b32 v3, v73, v2
	s_lshr_b32 s0, s46, 3
	s_cmpk_eq_i32 s87, 0x7440
	s_waitcnt lgkmcnt(0)
	v_max_f32_e32 v3, v3, v3
	v_max_f32_e32 v2, v2, v3
	ds_bpermute_b32 v3, v74, v2
	s_waitcnt lgkmcnt(0)
	v_max_f32_e32 v3, v3, v3
	v_max_f32_e32 v2, v2, v3
	v_sub_f32_e32 v20, v117, v2
	v_mul_f32_e32 v20, 0x3fb8aa3b, v20
	v_exp_f32_e32 v115, v20
	v_sub_f32_e32 v20, v106, v2
	v_mul_f32_e32 v20, 0x3fb8aa3b, v20
	v_exp_f32_e32 v118, v20
	v_sub_f32_e32 v20, v120, v2
	v_mul_f32_e32 v20, 0x3fb8aa3b, v20
	v_exp_f32_e32 v128, v20
	v_sub_f32_e32 v20, v108, v2
	v_mul_f32_e32 v20, 0x3fb8aa3b, v20
	v_exp_f32_e32 v129, v20
	v_sub_f32_e32 v20, v96, v2
	v_mul_f32_e32 v20, 0x3fb8aa3b, v20
	v_exp_f32_e32 v130, v20
	v_sub_f32_e32 v20, v97, v2
	v_mul_f32_e32 v20, 0x3fb8aa3b, v20
	v_exp_f32_e32 v131, v20
	v_sub_f32_e32 v20, v102, v2
	v_mul_f32_e32 v20, 0x3fb8aa3b, v20
	v_exp_f32_e32 v142, v20
	v_sub_f32_e32 v20, v103, v2
	v_mul_f32_e32 v20, 0x3fb8aa3b, v20
	v_exp_f32_e32 v143, v20
	v_sub_f32_e32 v20, v104, v2
	v_mul_f32_e32 v20, 0x3fb8aa3b, v20
	v_exp_f32_e32 v144, v20
	v_sub_f32_e32 v20, v105, v2
	v_mul_f32_e32 v20, 0x3fb8aa3b, v20
	v_exp_f32_e32 v145, v20
	v_sub_f32_e32 v20, v98, v2
	v_mul_f32_e32 v20, 0x3fb8aa3b, v20
	v_exp_f32_e32 v146, v20
	v_sub_f32_e32 v20, v99, v2
	v_mul_f32_e32 v20, 0x3fb8aa3b, v20
	v_exp_f32_e32 v147, v20
	v_sub_f32_e32 v20, v100, v2
	v_mul_f32_e32 v20, 0x3fb8aa3b, v20
	v_exp_f32_e32 v148, v20
	v_sub_f32_e32 v20, v101, v2
	v_mul_f32_e32 v20, 0x3fb8aa3b, v20
	v_exp_f32_e32 v149, v20
	v_sub_f32_e32 v20, v86, v2
	v_mul_f32_e32 v20, 0x3fb8aa3b, v20
	v_exp_f32_e32 v152, v20
	v_sub_f32_e32 v20, v88, v2
	v_mul_f32_e32 v20, 0x3fb8aa3b, v20
	v_exp_f32_e32 v153, v20
	v_sub_f32_e32 v20, v90, v2
	v_mul_f32_e32 v20, 0x3fb8aa3b, v20
	v_exp_f32_e32 v154, v20
	v_sub_f32_e32 v20, v44, v2
	v_mul_f32_e32 v20, 0x3fb8aa3b, v20
	v_exp_f32_e32 v155, v20
	v_sub_f32_e32 v20, v92, v2
	v_mul_f32_e32 v20, 0x3fb8aa3b, v20
	v_exp_f32_e32 v156, v20
	v_sub_f32_e32 v20, v46, v2
	v_mul_f32_e32 v20, 0x3fb8aa3b, v20
	v_exp_f32_e32 v157, v20
	v_sub_f32_e32 v20, v42, v2
	v_mul_f32_e32 v20, 0x3fb8aa3b, v20
	v_exp_f32_e32 v158, v20
	v_sub_f32_e32 v20, v43, v2
	v_mul_f32_e32 v20, 0x3fb8aa3b, v20
	v_exp_f32_e32 v159, v20
	v_sub_f32_e32 v20, v87, v2
	v_mul_f32_e32 v20, 0x3fb8aa3b, v20
	v_exp_f32_e32 v160, v20
	v_sub_f32_e32 v20, v89, v2
	v_mul_f32_e32 v20, 0x3fb8aa3b, v20
	v_exp_f32_e32 v161, v20
	v_sub_f32_e32 v20, v91, v2
	v_mul_f32_e32 v20, 0x3fb8aa3b, v20
	v_exp_f32_e32 v162, v20
	v_sub_f32_e32 v20, v45, v2
	v_mul_f32_e32 v20, 0x3fb8aa3b, v20
	v_exp_f32_e32 v163, v20
	v_sub_f32_e32 v20, v93, v2
	v_mul_f32_e32 v20, 0x3fb8aa3b, v20
	v_exp_f32_e32 v164, v20
	v_sub_f32_e32 v20, v47, v2
	v_mul_f32_e32 v20, 0x3fb8aa3b, v20
	v_exp_f32_e32 v165, v20
	v_sub_f32_e32 v20, v94, v2
	v_mul_f32_e32 v20, 0x3fb8aa3b, v20
	v_exp_f32_e32 v166, v20
	v_sub_f32_e32 v20, v95, v2
	v_mul_f32_e32 v20, 0x3fb8aa3b, v20
	v_exp_f32_e32 v167, v20
	v_sub_f32_e32 v20, v107, v2
	v_mul_f32_e32 v20, 0x3fb8aa3b, v20
	v_exp_f32_e32 v168, v20
	v_sub_f32_e32 v20, v34, v2
	v_mul_f32_e32 v20, 0x3fb8aa3b, v20
	v_exp_f32_e32 v169, v20
	v_sub_f32_e32 v20, v36, v2
	v_sub_f32_e32 v3, v50, v2
	v_mul_f32_e32 v20, 0x3fb8aa3b, v20
	v_mul_f32_e32 v3, 0x3fb8aa3b, v3
	v_sub_f32_e32 v7, v114, v2
	v_exp_f32_e32 v170, v20
	v_sub_f32_e32 v20, v109, v2
	v_exp_f32_e32 v3, v3
	v_mul_f32_e32 v7, 0x3fb8aa3b, v7
	v_mul_f32_e32 v20, 0x3fb8aa3b, v20
	v_exp_f32_e32 v7, v7
	v_exp_f32_e32 v171, v20
	v_sub_f32_e32 v20, v38, v2
	v_mul_f32_e32 v20, 0x3fb8aa3b, v20
	v_exp_f32_e32 v172, v20
	v_sub_f32_e32 v20, v110, v2
	v_add_f32_e32 v19, 0, v3
	v_mul_f32_e32 v20, 0x3fb8aa3b, v20
	v_add_f32_e32 v19, v7, v19
	v_exp_f32_e32 v173, v20
	v_sub_f32_e32 v20, v40, v2
	v_add_f32_e32 v19, v115, v19
	v_mul_f32_e32 v20, 0x3fb8aa3b, v20
; __device__ __forceinline__ unsigned pk2(float lo, float hi) { unsigned r; asm("v_cvt_pk_bf16_f32 %0, %1, %2" : "=v"(r) : "v"(lo), "v"(hi)); return r; }
; __device__ __forceinline__ void na_phase(const Frame& F, const bf16* QH, const bf16* VB, const float* rpb, bf16* U) {
;     ...
;             float sum = 0.f;
; #pragma unroll
;             for (int blk = 0; blk < 16; ++blk)
; #pragma unroll
;                 for (int e = 0; e < 4; ++e) { const float p = __builtin_amdgcn_exp2f((acc[blk][e] - mx) * 1.44269504089f); acc[blk][e] = p; sum += p; }
;             sum += __shfl_xor(sum, 16); sum += __shfl_xor(sum, 32);
;             const float inv = 1.0f / sum;
;             f32x4 o[4];
; #pragma unroll
;             for (int db = 0; db < 4; ++db) o[db] = (f32x4){0.f, 0.f, 0.f, 0.f};
; #pragma unroll
;             for (int i = 0; i < 8; ++i) {
;                 v4u pw; pw.x = pk2(acc[2 * i][0], acc[2 * i][1]); pw.y = pk2(acc[2 * i][2], acc[2 * i][3]); pw.z = pk2(acc[2 * i + 1][0], acc[2 * i + 1][1]); pw.w = pk2(acc[2 * i + 1][2], acc[2 * i + 1][3]);
;                 const bf16x8 pf = __builtin_bit_cast(bf16x8, pw);
;                 const size_t vrow = (((size_t)h * 512 + b * 256 + rs + i) * 8 + (c0 >> 3) + q4) * 512;
; #pragma unroll
;                 for (int db = 0; db < 4; ++db) { const bf16x8 vfrag = *(const bf16x8*)(VB + vrow + (16 * db + n) * 8);
;                     o[db] = __builtin_amdgcn_mfma_f32_16x16x32_bf16(vfrag, pf, o[db], 0, 0, 0); }
	v_add_f32_e32 v19, v118, v19
	v_exp_f32_e32 v174, v20
	v_sub_f32_e32 v20, v111, v2
	v_add_f32_e32 v19, v128, v19
	v_mul_f32_e32 v20, 0x3fb8aa3b, v20
	v_add_f32_e32 v19, v129, v19
	v_exp_f32_e32 v175, v20
	v_sub_f32_e32 v20, v123, v2
	v_add_lshl_u32 v50, s0, v72, 10
	v_add_f32_e32 v19, v130, v19
	v_mul_f32_e32 v24, 0x3fb8aa3b, v20
	v_lshl_add_u64 v[20:21], v[60:61], 0, v[50:51]
	v_sub_f32_e32 v28, v35, v2
	v_add_f32_e32 v19, v131, v19
	v_lshl_add_u64 v[150:151], s[70:71], 0, v[20:21]
	v_mul_f32_e32 v34, 0x3fb8aa3b, v28
	v_add_f32_e32 v19, v142, v19
	v_add_co_u32_e32 v32, vcc, s78, v150
	v_exp_f32_e32 v176, v34
	v_sub_f32_e32 v34, v37, v2
	v_add_f32_e32 v19, v143, v19
	v_addc_co_u32_e32 v33, vcc, 0, v151, vcc
	v_mul_f32_e32 v34, 0x3fb8aa3b, v34
	v_add_f32_e32 v19, v144, v19
	s_mov_b64 exec, s[92:93]
	global_load_dwordx4 v[20:23], v[32:33], off
	s_mov_b64 exec, s[98:99]
	v_mov_b32_e32 v20, 0
	v_mov_b32_e32 v21, 0
	v_mov_b32_e32 v22, 0
	v_mov_b32_e32 v23, 0
	s_mov_b64 exec, -1
	v_exp_f32_e32 v50, v24
	s_mov_b64 exec, s[92:93]
	global_load_dwordx4 v[24:27], v[32:33], off offset:256
	s_mov_b64 exec, s[98:99]
	v_mov_b32_e32 v24, 0
	v_mov_b32_e32 v25, 0
	v_mov_b32_e32 v26, 0
	v_mov_b32_e32 v27, 0
	s_mov_b64 exec, -1
	v_exp_f32_e32 v177, v34
	v_sub_f32_e32 v34, v124, v2
	v_add_co_u32_e32 v86, vcc, s79, v150
	v_add_f32_e32 v19, v145, v19
	v_mul_f32_e32 v36, 0x3fb8aa3b, v34
	v_addc_co_u32_e32 v87, vcc, 0, v151, vcc
	v_add_f32_e32 v19, v146, v19
	s_mov_b64 exec, s[92:93]
	global_load_dwordx4 v[28:31], v[32:33], off offset:512
	s_mov_b64 exec, s[98:99]
	v_mov_b32_e32 v28, 0
	v_mov_b32_e32 v29, 0
	v_mov_b32_e32 v30, 0
	v_mov_b32_e32 v31, 0
	s_mov_b64 exec, -1
	v_exp_f32_e32 v178, v36
	s_mov_b64 exec, s[92:93]
	global_load_dwordx4 v[36:39], v[86:87], off
	s_mov_b64 exec, s[98:99]
	v_mov_b32_e32 v36, 0
	v_mov_b32_e32 v37, 0
	v_mov_b32_e32 v38, 0
	v_mov_b32_e32 v39, 0
	s_mov_b64 exec, -1
	v_sub_f32_e32 v44, v125, v2
	s_mov_b64 exec, s[92:93]
	global_load_dwordx4 v[32:35], v[32:33], off offset:768
	s_mov_b64 exec, s[98:99]
	v_mov_b32_e32 v32, 0
	v_mov_b32_e32 v33, 0
	v_mov_b32_e32 v34, 0
	v_mov_b32_e32 v35, 0
	s_mov_b64 exec, -1
	v_add_f32_e32 v19, v147, v19
	v_mul_f32_e32 v44, 0x3fb8aa3b, v44
	v_add_f32_e32 v19, v148, v19
	s_mov_b64 exec, s[92:93]
	global_load_dwordx4 v[40:43], v[86:87], off offset:256
	s_mov_b64 exec, s[98:99]
	v_mov_b32_e32 v40, 0
	v_mov_b32_e32 v41, 0
	v_mov_b32_e32 v42, 0
	v_mov_b32_e32 v43, 0
	s_mov_b64 exec, -1
	v_exp_f32_e32 v179, v44
	v_sub_f32_e32 v44, v126, v2
	v_sub_f32_e32 v88, v127, v2
	v_add_co_u32_e32 v102, vcc, s80, v150
	v_add_f32_e32 v19, v149, v19
	v_mul_f32_e32 v44, 0x3fb8aa3b, v44
	v_mul_f32_e32 v88, 0x3fb8aa3b, v88
	v_addc_co_u32_e32 v103, vcc, 0, v151, vcc
	v_add_f32_e32 v19, v152, v19
	v_exp_f32_e32 v180, v44
	s_mov_b64 exec, s[92:93]
	global_load_dwordx4 v[44:47], v[86:87], off offset:512
	s_mov_b64 exec, s[98:99]
	v_mov_b32_e32 v44, 0
	v_mov_b32_e32 v45, 0
	v_mov_b32_e32 v46, 0
	v_mov_b32_e32 v47, 0
	s_mov_b64 exec, -1
	s_mov_b64 exec, s[92:93]
	global_load_dwordx4 v[90:93], v[102:103], off
	s_mov_b64 exec, s[98:99]
	v_mov_b32_e32 v90, 0
	v_mov_b32_e32 v91, 0
	v_mov_b32_e32 v92, 0
	v_mov_b32_e32 v93, 0
	s_mov_b64 exec, -1
	v_exp_f32_e32 v181, v88
	s_mov_b64 exec, s[92:93]
	global_load_dwordx4 v[86:89], v[86:87], off offset:768
	s_mov_b64 exec, s[98:99]
	v_mov_b32_e32 v86, 0
	v_mov_b32_e32 v87, 0
	v_mov_b32_e32 v88, 0
	v_mov_b32_e32 v89, 0
	s_mov_b64 exec, -1
	v_add_f32_e32 v19, v153, v19
	v_add_f32_e32 v19, v154, v19
	v_add_f32_e32 v19, v155, v19
	v_add_f32_e32 v19, v156, v19
	v_add_f32_e32 v19, v157, v19
	v_add_f32_e32 v19, v158, v19
	v_add_f32_e32 v19, v159, v19
	v_add_f32_e32 v19, v160, v19
	v_add_f32_e32 v19, v161, v19
	v_add_f32_e32 v19, v162, v19
	v_add_f32_e32 v19, v163, v19
	v_add_f32_e32 v19, v164, v19
	v_add_f32_e32 v19, v165, v19
	v_add_f32_e32 v19, v166, v19
	v_add_f32_e32 v19, v167, v19
	v_add_f32_e32 v19, v168, v19
	v_add_f32_e32 v19, v169, v19
	v_add_f32_e32 v19, v170, v19
	v_add_f32_e32 v19, v171, v19
	v_add_f32_e32 v19, v172, v19
	v_add_f32_e32 v19, v173, v19
	s_mov_b64 exec, s[92:93]
	global_load_dwordx4 v[98:101], v[102:103], off offset:512
	s_mov_b64 exec, s[98:99]
	v_mov_b32_e32 v98, 0
	v_mov_b32_e32 v99, 0
	v_mov_b32_e32 v100, 0
	v_mov_b32_e32 v101, 0
	s_mov_b64 exec, -1
	v_add_f32_e32 v19, v174, v19
	v_add_f32_e32 v19, v175, v19
	v_add_f32_e32 v19, v50, v19
	v_add_f32_e32 v19, v176, v19
	v_sub_f32_e32 v94, v112, v2
	v_add_f32_e32 v19, v177, v19
	v_mul_f32_e32 v94, 0x3fb8aa3b, v94
	v_sub_f32_e32 v16, v16, v2
	v_add_f32_e32 v19, v178, v19
	v_exp_f32_e32 v182, v94
	v_mul_f32_e32 v16, 0x3fb8aa3b, v16
	v_add_f32_e32 v19, v179, v19
	s_mov_b64 exec, s[92:93]
	global_load_dwordx4 v[94:97], v[102:103], off offset:256
	s_mov_b64 exec, s[98:99]
	v_mov_b32_e32 v94, 0
	v_mov_b32_e32 v95, 0
	v_mov_b32_e32 v96, 0
	v_mov_b32_e32 v97, 0
	s_mov_b64 exec, -1
	v_exp_f32_e32 v183, v16
	v_add_f32_e32 v19, v180, v19
	v_add_f32_e32 v19, v181, v19
	v_sub_f32_e32 v16, v17, v2
	v_sub_f32_e32 v107, v18, v2
	v_add_co_u32_e32 v116, vcc, s81, v150
	v_add_f32_e32 v106, v182, v19
	v_mul_f32_e32 v16, 0x3fb8aa3b, v16
	v_addc_co_u32_e32 v117, vcc, 0, v151, vcc
	v_mul_f32_e32 v107, 0x3fb8aa3b, v107
	v_exp_f32_e32 v184, v16
	s_mov_b64 exec, s[92:93]
	global_load_dwordx4 v[16:19], v[116:117], off
	s_mov_b64 exec, s[98:99]
	v_mov_b32_e32 v16, 0
	v_mov_b32_e32 v17, 0
	v_mov_b32_e32 v18, 0
	v_mov_b32_e32 v19, 0
	s_mov_b64 exec, -1
	v_exp_f32_e32 v185, v107
	s_mov_b64 exec, s[92:93]
	global_load_dwordx4 v[102:105], v[102:103], off offset:768
	s_mov_b64 exec, s[98:99]
	v_mov_b32_e32 v102, 0
	v_mov_b32_e32 v103, 0
	v_mov_b32_e32 v104, 0
	v_mov_b32_e32 v105, 0
	s_mov_b64 exec, -1
	v_add_f32_e32 v110, v183, v106
	s_mov_b64 exec, s[92:93]
	global_load_dwordx4 v[106:109], v[116:117], off offset:256
	s_mov_b64 exec, s[98:99]
	v_mov_b32_e32 v106, 0
	v_mov_b32_e32 v107, 0
	v_mov_b32_e32 v108, 0
	v_mov_b32_e32 v109, 0
	s_mov_b64 exec, -1
	v_add_f32_e32 v110, v184, v110
	v_add_f32_e32 v132, v185, v110
	s_mov_b64 exec, s[92:93]
	global_load_dwordx4 v[110:113], v[116:117], off offset:512
	s_mov_b64 exec, s[98:99]
	v_mov_b32_e32 v110, 0
	v_mov_b32_e32 v111, 0
	v_mov_b32_e32 v112, 0
	v_mov_b32_e32 v113, 0
	s_mov_b64 exec, -1
	v_cvt_pk_bf16_f32 v114, v3, v7
	v_cvt_pk_bf16_f32 v115, v115, v118
	s_mov_b64 exec, s[92:93]
	global_load_dwordx4 v[118:121], v[116:117], off offset:768
	s_mov_b64 exec, s[98:99]
	v_mov_b32_e32 v118, 0
	v_mov_b32_e32 v119, 0
	v_mov_b32_e32 v120, 0
	v_mov_b32_e32 v121, 0
	s_mov_b64 exec, -1
	v_add_co_u32_e32 v134, vcc, s82, v150
	v_cvt_pk_bf16_f32 v116, v128, v129
	v_cvt_pk_bf16_f32 v117, v130, v131
	v_sub_f32_e32 v15, v15, v2
	s_waitcnt vmcnt(15)
; __device__ __forceinline__ unsigned pk2(float lo, float hi) { unsigned r; asm("v_cvt_pk_bf16_f32 %0, %1, %2" : "=v"(r) : "v"(lo), "v"(hi)); return r; }
; __device__ __forceinline__ void na_phase(const Frame& F, const bf16* QH, const bf16* VB, const float* rpb, bf16* U) {
;     ...
;                 for (int e = 0; e < 4; ++e) { const float p = __builtin_amdgcn_exp2f((acc[blk][e] - mx) * 1.44269504089f); acc[blk][e] = p; sum += p; }
;             sum += __shfl_xor(sum, 16); sum += __shfl_xor(sum, 32);
;             const float inv = 1.0f / sum;
;             f32x4 o[4];
; #pragma unroll
;             for (int db = 0; db < 4; ++db) o[db] = (f32x4){0.f, 0.f, 0.f, 0.f};
; #pragma unroll
;             for (int i = 0; i < 8; ++i) {
;                 v4u pw; pw.x = pk2(acc[2 * i][0], acc[2 * i][1]); pw.y = pk2(acc[2 * i][2], acc[2 * i][3]); pw.z = pk2(acc[2 * i + 1][0], acc[2 * i + 1][1]); pw.w = pk2(acc[2 * i + 1][2], acc[2 * i + 1][3]);
;                 const bf16x8 pf = __builtin_bit_cast(bf16x8, pw);
;                 const size_t vrow = (((size_t)h * 512 + b * 256 + rs + i) * 8 + (c0 >> 3) + q4) * 512;
; #pragma unroll
;                 for (int db = 0; db < 4; ++db) { const bf16x8 vfrag = *(const bf16x8*)(VB + vrow + (16 * db + n) * 8);
;                     o[db] = __builtin_amdgcn_mfma_f32_16x16x32_bf16(vfrag, pf, o[db], 0, 0, 0); }
;             }
	v_mfma_f32_16x16x32_bf16 v[20:23], v[20:23], v[114:117], 0
	v_addc_co_u32_e32 v135, vcc, 0, v151, vcc
	v_mul_f32_e32 v15, 0x3fb8aa3b, v15
	s_waitcnt vmcnt(14)
	v_mfma_f32_16x16x32_bf16 v[24:27], v[24:27], v[114:117], 0
	v_sub_f32_e32 v7, v14, v2
	v_add_co_u32_e32 v14, vcc, s83, v150
	s_waitcnt vmcnt(11)
	v_mfma_f32_16x16x32_bf16 v[32:35], v[32:35], v[114:117], 0
	v_exp_f32_e32 v186, v15
	v_addc_co_u32_e32 v15, vcc, 0, v151, vcc
	v_mfma_f32_16x16x32_bf16 v[28:31], v[28:31], v[114:117], 0
	s_mov_b64 exec, s[92:93]
	global_load_dwordx4 v[138:141], v[14:15], off
	s_mov_b64 exec, s[98:99]
	v_mov_b32_e32 v138, 0
	v_mov_b32_e32 v139, 0
	v_mov_b32_e32 v140, 0
	v_mov_b32_e32 v141, 0
	s_mov_b64 exec, -1
	v_cvt_pk_bf16_f32 v114, v142, v143
	v_cvt_pk_bf16_f32 v115, v144, v145
	s_mov_b64 exec, s[92:93]
	global_load_dwordx4 v[142:145], v[14:15], off offset:256
	s_mov_b64 exec, s[98:99]
	v_mov_b32_e32 v142, 0
	v_mov_b32_e32 v143, 0
	v_mov_b32_e32 v144, 0
	v_mov_b32_e32 v145, 0
	s_mov_b64 exec, -1
	v_cvt_pk_bf16_f32 v116, v146, v147
	v_cvt_pk_bf16_f32 v117, v148, v149
	s_mov_b64 exec, s[92:93]
	global_load_dwordx4 v[122:125], v[134:135], off
	s_mov_b64 exec, s[98:99]
	v_mov_b32_e32 v122, 0
	v_mov_b32_e32 v123, 0
	v_mov_b32_e32 v124, 0
	v_mov_b32_e32 v125, 0
	s_mov_b64 exec, -1
	s_mov_b64 exec, s[92:93]
	global_load_dwordx4 v[126:129], v[134:135], off offset:256
	s_mov_b64 exec, s[98:99]
	v_mov_b32_e32 v126, 0
	v_mov_b32_e32 v127, 0
	v_mov_b32_e32 v128, 0
	v_mov_b32_e32 v129, 0
	s_mov_b64 exec, -1
	s_nop 1
	v_mfma_f32_16x16x32_bf16 v[20:23], v[36:39], v[114:117], v[20:23]
	s_mov_b64 exec, s[92:93]
	global_load_dwordx4 v[36:39], v[14:15], off offset:512
	s_mov_b64 exec, s[98:99]
	v_mov_b32_e32 v36, 0
	v_mov_b32_e32 v37, 0
	v_mov_b32_e32 v38, 0
	v_mov_b32_e32 v39, 0
	s_mov_b64 exec, -1
	v_add_f32_e32 v3, v186, v132
	s_mov_b64 exec, s[92:93]
	global_load_dwordx4 v[130:133], v[134:135], off offset:512
	s_mov_b64 exec, s[98:99]
	v_mov_b32_e32 v130, 0
	v_mov_b32_e32 v131, 0
	v_mov_b32_e32 v132, 0
	v_mov_b32_e32 v133, 0
	s_mov_b64 exec, -1
	s_waitcnt vmcnt(16)
	v_mfma_f32_16x16x32_bf16 v[24:27], v[40:43], v[114:117], v[24:27]
	s_mov_b64 exec, s[92:93]
	global_load_dwordx4 v[40:43], v[14:15], off offset:768
	s_mov_b64 exec, s[98:99]
	v_mov_b32_e32 v40, 0
	v_mov_b32_e32 v41, 0
	v_mov_b32_e32 v42, 0
	v_mov_b32_e32 v43, 0
	s_mov_b64 exec, -1
	v_add_co_u32_e32 v14, vcc, s84, v150
	s_waitcnt vmcnt(14)
	v_mfma_f32_16x16x32_bf16 v[32:35], v[86:89], v[114:117], v[32:35]
	v_addc_co_u32_e32 v15, vcc, 0, v151, vcc
	v_cvt_pk_bf16_f32 v87, v154, v155
	v_add_co_u32_e32 v154, vcc, s85, v150
	v_cvt_pk_bf16_f32 v86, v152, v153
	s_mov_b64 exec, s[92:93]
	global_load_dwordx4 v[146:149], v[14:15], off
	s_mov_b64 exec, s[98:99]
	v_mov_b32_e32 v146, 0
	v_mov_b32_e32 v147, 0
	v_mov_b32_e32 v148, 0
	v_mov_b32_e32 v149, 0
	s_mov_b64 exec, -1
	s_nop 0
	v_addc_co_u32_e32 v155, vcc, 0, v151, vcc
	s_mov_b64 exec, s[92:93]
	global_load_dwordx4 v[150:153], v[154:155], off
	s_mov_b64 exec, s[98:99]
	v_mov_b32_e32 v150, 0
	v_mov_b32_e32 v151, 0
	v_mov_b32_e32 v152, 0
	v_mov_b32_e32 v153, 0
	s_mov_b64 exec, -1
	s_nop 1
	v_mfma_f32_16x16x32_bf16 v[28:31], v[44:47], v[114:117], v[28:31]
	s_mov_b64 exec, s[92:93]
	global_load_dwordx4 v[134:137], v[134:135], off offset:768
	s_mov_b64 exec, s[98:99]
	v_mov_b32_e32 v134, 0
	v_mov_b32_e32 v135, 0
	v_mov_b32_e32 v136, 0
	v_mov_b32_e32 v137, 0
	s_mov_b64 exec, -1
	v_cvt_pk_bf16_f32 v88, v156, v157
	s_mov_b64 exec, s[92:93]
	global_load_dwordx4 v[44:47], v[14:15], off offset:256
	s_mov_b64 exec, s[98:99]
	v_mov_b32_e32 v44, 0
	v_mov_b32_e32 v45, 0
	v_mov_b32_e32 v46, 0
	v_mov_b32_e32 v47, 0
	s_mov_b64 exec, -1
	s_mov_b64 exec, s[92:93]
	global_load_dwordx4 v[114:117], v[14:15], off offset:512
	s_mov_b64 exec, s[98:99]
	v_mov_b32_e32 v114, 0
	v_mov_b32_e32 v115, 0
	v_mov_b32_e32 v116, 0
	v_mov_b32_e32 v117, 0
	s_mov_b64 exec, -1
	v_cvt_pk_bf16_f32 v89, v158, v159
	v_mul_f32_e32 v7, 0x3fb8aa3b, v7
	v_mfma_f32_16x16x32_bf16 v[20:23], v[90:93], v[86:89], v[20:23]
	s_mov_b64 exec, s[92:93]
	global_load_dwordx4 v[90:93], v[14:15], off offset:768
	s_mov_b64 exec, s[98:99]
	v_mov_b32_e32 v90, 0
	v_mov_b32_e32 v91, 0
	v_mov_b32_e32 v92, 0
	v_mov_b32_e32 v93, 0
	s_mov_b64 exec, -1
	v_exp_f32_e32 v187, v7
	v_sub_f32_e32 v7, v13, v2
	v_mul_f32_e32 v7, 0x3fb8aa3b, v7
	v_exp_f32_e32 v188, v7
	v_sub_f32_e32 v7, v12, v2
	s_waitcnt vmcnt(19)
	v_mfma_f32_16x16x32_bf16 v[12:15], v[98:101], v[86:89], v[28:31]
	v_mul_f32_e32 v7, 0x3fb8aa3b, v7
	v_exp_f32_e32 v156, v7
	v_sub_f32_e32 v7, v11, v2
	s_mov_b64 exec, s[92:93]
	global_load_dwordx4 v[28:31], v[154:155], off offset:256
	s_mov_b64 exec, s[98:99]
	v_mov_b32_e32 v28, 0
	v_mov_b32_e32 v29, 0
	v_mov_b32_e32 v30, 0
	v_mov_b32_e32 v31, 0
	s_mov_b64 exec, -1
	s_waitcnt vmcnt(19)
	v_mfma_f32_16x16x32_bf16 v[24:27], v[94:97], v[86:89], v[24:27]
	s_mov_b64 exec, s[92:93]
	global_load_dwordx4 v[94:97], v[154:155], off offset:512
	s_mov_b64 exec, s[98:99]
	v_mov_b32_e32 v94, 0
	v_mov_b32_e32 v95, 0
	v_mov_b32_e32 v96, 0
	v_mov_b32_e32 v97, 0
	s_mov_b64 exec, -1
	v_mul_f32_e32 v7, 0x3fb8aa3b, v7
	v_exp_f32_e32 v98, v7
	s_waitcnt vmcnt(18)
; __device__ __forceinline__ unsigned pk2(float lo, float hi) { unsigned r; asm("v_cvt_pk_bf16_f32 %0, %1, %2" : "=v"(r) : "v"(lo), "v"(hi)); return r; }
; __device__ __forceinline__ void na_phase(const Frame& F, const bf16* QH, const bf16* VB, const float* rpb, bf16* U) {
;     ...
;                 for (int e = 0; e < 4; ++e) { const float p = __builtin_amdgcn_exp2f((acc[blk][e] - mx) * 1.44269504089f); acc[blk][e] = p; sum += p; }
;             sum += __shfl_xor(sum, 16); sum += __shfl_xor(sum, 32);
;             const float inv = 1.0f / sum;
;             f32x4 o[4];
; #pragma unroll
;             for (int db = 0; db < 4; ++db) o[db] = (f32x4){0.f, 0.f, 0.f, 0.f};
; #pragma unroll
;             for (int i = 0; i < 8; ++i) {
;                 v4u pw; pw.x = pk2(acc[2 * i][0], acc[2 * i][1]); pw.y = pk2(acc[2 * i][2], acc[2 * i][3]); pw.z = pk2(acc[2 * i + 1][0], acc[2 * i + 1][1]); pw.w = pk2(acc[2 * i + 1][2], acc[2 * i + 1][3]);
;                 const bf16x8 pf = __builtin_bit_cast(bf16x8, pw);
;                 const size_t vrow = (((size_t)h * 512 + b * 256 + rs + i) * 8 + (c0 >> 3) + q4) * 512;
; #pragma unroll
;                 for (int db = 0; db < 4; ++db) { const bf16x8 vfrag = *(const bf16x8*)(VB + vrow + (16 * db + n) * 8);
;                     o[db] = __builtin_amdgcn_mfma_f32_16x16x32_bf16(vfrag, pf, o[db], 0, 0, 0); }
;             }
; #pragma unroll
;             for (int db = 0; db < 4; ++db) { v2u w; w.x = pk2(o[db][0] * inv, o[db][1] * inv); w.y = pk2(o[db][2] * inv, o[db][3] * inv);
;                 *(v2u*)(U + tokq * DM + h * 64 + 16 * db + 4 * q4) = w; }
	v_mfma_f32_16x16x32_bf16 v[32:35], v[102:105], v[86:89], v[32:35]
	v_cvt_pk_bf16_f32 v86, v160, v161
	v_cvt_pk_bf16_f32 v87, v162, v163
	v_cvt_pk_bf16_f32 v88, v164, v165
	v_cvt_pk_bf16_f32 v89, v166, v167
	v_sub_f32_e32 v7, v10, v2
	v_mfma_f32_16x16x32_bf16 v[16:19], v[16:19], v[86:89], v[20:23]
	v_mul_f32_e32 v7, 0x3fb8aa3b, v7
	v_exp_f32_e32 v99, v7
	v_sub_f32_e32 v7, v9, v2
	s_waitcnt vmcnt(17)
	v_mfma_f32_16x16x32_bf16 v[20:23], v[106:109], v[86:89], v[24:27]
	v_mul_f32_e32 v7, 0x3fb8aa3b, v7
	v_add_f32_e32 v3, v187, v3
	v_exp_f32_e32 v100, v7
	s_mov_b64 exec, s[92:93]
	global_load_dwordx4 v[24:27], v[154:155], off offset:768
	s_mov_b64 exec, s[98:99]
	v_mov_b32_e32 v24, 0
	v_mov_b32_e32 v25, 0
	v_mov_b32_e32 v26, 0
	v_mov_b32_e32 v27, 0
	s_mov_b64 exec, -1
	s_waitcnt vmcnt(17)
	v_mfma_f32_16x16x32_bf16 v[10:13], v[110:113], v[86:89], v[12:15]
	v_sub_f32_e32 v7, v8, v2
	v_add_f32_e32 v3, v188, v3
	v_mul_f32_e32 v7, 0x3fb8aa3b, v7
	s_waitcnt vmcnt(16)
	v_mfma_f32_16x16x32_bf16 v[32:35], v[118:121], v[86:89], v[32:35]
	v_sub_f32_e32 v6, v6, v2
	v_add_f32_e32 v3, v156, v3
	v_exp_f32_e32 v101, v7
	v_mul_f32_e32 v6, 0x3fb8aa3b, v6
	v_sub_f32_e32 v5, v5, v2
	v_cvt_pk_bf16_f32 v86, v168, v169
	v_add_f32_e32 v3, v98, v3
	v_exp_f32_e32 v102, v6
	v_mul_f32_e32 v5, 0x3fb8aa3b, v5
	v_cvt_pk_bf16_f32 v87, v170, v171
	v_cvt_pk_bf16_f32 v88, v172, v173
	v_cvt_pk_bf16_f32 v89, v174, v175
	v_add_f32_e32 v3, v99, v3
	s_waitcnt vmcnt(13)
	v_mfma_f32_16x16x32_bf16 v[14:17], v[122:125], v[86:89], v[16:19]
	v_add_f32_e32 v3, v100, v3
	v_add_f32_e32 v3, v101, v3
	v_add_f32_e32 v3, v102, v3
	s_waitcnt vmcnt(12)
	v_mfma_f32_16x16x32_bf16 v[18:21], v[126:129], v[86:89], v[20:23]
	v_sub_f32_e32 v1, v1, v2
	v_mul_f32_e32 v1, 0x3fb8aa3b, v1
	v_sub_f32_e32 v0, v0, v2
	s_waitcnt vmcnt(10)
	v_mfma_f32_16x16x32_bf16 v[8:11], v[130:133], v[86:89], v[10:13]
	v_mul_f32_e32 v0, 0x3fb8aa3b, v0
	v_lshl_add_u64 v[60:61], v[60:61], 0, s[48:49]
	s_waitcnt vmcnt(6)
	v_mfma_f32_16x16x32_bf16 v[32:35], v[134:137], v[86:89], v[32:35]
	v_cvt_pk_bf16_f32 v86, v50, v176
	v_exp_f32_e32 v50, v5
	v_cvt_pk_bf16_f32 v87, v177, v178
	v_cvt_pk_bf16_f32 v88, v179, v180
	v_cvt_pk_bf16_f32 v89, v181, v182
	s_nop 0
	v_add_f32_e32 v5, v50, v3
	v_sub_f32_e32 v3, v4, v2
	v_mfma_f32_16x16x32_bf16 v[12:15], v[138:141], v[86:89], v[14:17]
	v_mul_f32_e32 v3, 0x3fb8aa3b, v3
	v_mfma_f32_16x16x32_bf16 v[6:9], v[36:39], v[86:89], v[8:11]
	v_exp_f32_e32 v36, v3
	v_exp_f32_e32 v37, v1
	v_exp_f32_e32 v38, v0
	v_mfma_f32_16x16x32_bf16 v[16:19], v[142:145], v[86:89], v[18:21]
	v_add_f32_e32 v4, v36, v5
	v_add_f32_e32 v4, v37, v4
	v_add_f32_e32 v39, v38, v4
	v_mfma_f32_16x16x32_bf16 v[20:23], v[40:43], v[86:89], v[32:35]
	v_cvt_pk_bf16_f32 v32, v183, v184
	v_cvt_pk_bf16_f32 v33, v185, v186
	v_cvt_pk_bf16_f32 v34, v187, v188
	v_cvt_pk_bf16_f32 v35, v156, v98
	s_nop 0
	v_mfma_f32_16x16x32_bf16 v[10:13], v[146:149], v[32:35], v[12:15]
	s_waitcnt vmcnt(5)
	v_mfma_f32_16x16x32_bf16 v[14:17], v[44:47], v[32:35], v[16:19]
	v_cvt_pk_bf16_f32 v18, v99, v100
	v_cvt_pk_bf16_f32 v19, v101, v102
	s_waitcnt vmcnt(4)
	v_mfma_f32_16x16x32_bf16 v[0:3], v[114:117], v[32:35], v[6:9]
	s_waitcnt vmcnt(3)
	v_mfma_f32_16x16x32_bf16 v[4:7], v[90:93], v[32:35], v[20:23]
	v_cvt_pk_bf16_f32 v20, v50, v36
	v_cvt_pk_bf16_f32 v21, v37, v38
	s_nop 0
	v_mfma_f32_16x16x32_bf16 v[8:11], v[150:153], v[18:21], v[10:13]
	s_nop 2
	ds_bpermute_b32 v12, v73, v39
	s_waitcnt vmcnt(1)
	v_mfma_f32_16x16x32_bf16 v[0:3], v[94:97], v[18:21], v[0:3]
	s_waitcnt lgkmcnt(0)
	v_add_f32_e32 v22, v39, v12
	v_mfma_f32_16x16x32_bf16 v[12:15], v[28:31], v[18:21], v[14:17]
	s_nop 2
	ds_bpermute_b32 v16, v74, v22
	s_waitcnt vmcnt(0)
	v_mfma_f32_16x16x32_bf16 v[4:7], v[24:27], v[18:21], v[4:7]
	s_waitcnt lgkmcnt(0)
	v_add_f32_e32 v16, v22, v16
	v_div_scale_f32 v17, s[0:1], v16, v16, 1.0
	v_rcp_f32_e32 v22, v17
	s_nop 0
	v_fma_f32 v18, -v17, v22, 1.0
	v_fmac_f32_e32 v22, v18, v22
	v_div_scale_f32 v18, vcc, 1.0, v16, 1.0
	v_mul_f32_e32 v19, v18, v22
	v_fma_f32 v20, -v17, v19, v18
	v_fmac_f32_e32 v19, v20, v22
	v_fma_f32 v17, -v17, v19, v18
	v_div_fmas_f32 v17, v17, v22, v19
	v_div_fixup_f32 v18, v17, v16, 1.0
	v_mul_f32_e32 v8, v18, v8
	v_mul_f32_e32 v9, v18, v9
	v_mul_f32_e32 v0, v18, v0
	v_mul_f32_e32 v1, v18, v1
	v_cvt_pk_bf16_f32 v8, v8, v9
	v_mul_f32_e32 v9, v18, v10
	v_cvt_pk_bf16_f32 v0, v0, v1
	v_mul_f32_e32 v1, v18, v2
	v_lshl_add_u64 v[16:17], s[70:71], 0, v[62:63]
	v_mul_f32_e32 v10, v18, v11
	v_cvt_pk_bf16_f32 v9, v9, v10
	v_mul_f32_e32 v2, v18, v3
	v_cvt_pk_bf16_f32 v1, v1, v2
	global_store_dwordx2 v[16:17], v[8:9], off offset:-64
	v_mul_f32_e32 v8, v18, v12
	v_mul_f32_e32 v9, v18, v13
	global_store_dwordx2 v[16:17], v[0:1], off
	v_mul_f32_e32 v0, v18, v4
	v_mul_f32_e32 v1, v18, v5
	v_cvt_pk_bf16_f32 v8, v8, v9
	v_mul_f32_e32 v9, v18, v14
	v_cvt_pk_bf16_f32 v0, v0, v1
	v_mul_f32_e32 v1, v18, v6
	v_lshl_add_u64 v[62:63], v[62:63], 0, s[50:51]
	v_mul_f32_e32 v10, v18, v15
	v_cvt_pk_bf16_f32 v9, v9, v10
	global_store_dwordx2 v[16:17], v[8:9], off offset:-32
	v_mul_f32_e32 v2, v18, v7
	v_cvt_pk_bf16_f32 v1, v1, v2
	global_store_dwordx2 v[16:17], v[0:1], off offset:32
	s_cbranch_scc1 .LBB0_904
